# grid barrier: last top-level arriver releases all XCD generation words directly; L1 invalidate issued at arrival (counted per XCD) instead of after release
# speedup vs baseline: 1.2165x; 1.0241x over previous
; __device__ __forceinline__ unsigned xb_ld(unsigned* p)              { return __hip_atomic_load(p, __ATOMIC_RELAXED, __HIP_MEMORY_SCOPE_AGENT); }
; __device__ __forceinline__ unsigned xb_add(unsigned* p, unsigned v) { return __hip_atomic_fetch_add(p, v, __ATOMIC_RELAXED, __HIP_MEMORY_SCOPE_AGENT); }
; #define XB_SPIN(cond, bar) do { unsigned _sp = 0; while (cond) { __builtin_amdgcn_s_sleep(1); \
;     if ((++_sp & 255u) == 0u) { if (xb_ld(&(bar)[XB_TMO])) break; if (_sp > XB_SPIN_CAP) { atomicAdd(&(bar)[XB_TMO], 1u); break; } } } } while (0)
; __device__ __forceinline__ void xcd_barrier(const XcdBarrier& b) {
;   asm volatile("s_waitcnt vmcnt(0)" ::: "memory");
;   __syncthreads();
;   if (threadIdx.x == 0) {
;     unsigned* bar = b.bar;
;     __builtin_amdgcn_s_waitcnt(0);
;     unsigned nloc = b.st[0], nx = b.st[1];
;     if (nloc == 0u) { xcd_barrier_complete(bar, b.x, nloc, nx); b.st[0] = nloc; b.st[1] = nx; }
;     const unsigned old = xb_add(&bar[XB_XSUB(b.x)], 1u);
;     const unsigned gen = old / nloc;
;     if (old + 1u == (gen + 1u) * nloc) {
;       __builtin_amdgcn_fence(__ATOMIC_RELEASE, "agent");
;       asm volatile("s_waitcnt vmcnt(0)" ::: "memory");
;       const unsigned og = xb_add(&bar[XB_TOP], 1u);
;       const unsigned tg = og / nx;
;       if (og + 1u == (tg + 1u) * nx) xb_add(&bar[XB_TOPGEN], 1u);
;       else XB_SPIN(xb_ld(&bar[XB_TOPGEN]) == tg, bar);
.LBB0_32:
	v_readlane_b32 s4, v229, 26
	s_lshl_b32 s4, s4, 6
	s_lshl_b64 s[8:9], s[4:5], 2
	s_add_u32 s8, s34, s8
	s_addc_u32 s9, s35, s9
	global_atomic_add v3, v198, v199, s[8:9] offset:1024 sc0
	v_cvt_f32_u32_e32 v1, v2
	v_sub_u32_e32 v4, 0, v2
	v_rcp_iflag_f32_e32 v1, v1
	s_nop 0
	v_mul_f32_e32 v1, 0x4f7ffffe, v1
	v_cvt_u32_f32_e32 v1, v1
	v_mul_lo_u32 v4, v4, v1
	v_mul_hi_u32 v4, v1, v4
	v_add_u32_e32 v1, v1, v4
	s_waitcnt vmcnt(0)
	buffer_inv sc1
	v_mul_hi_u32 v1, v3, v1
	v_mul_lo_u32 v4, v1, v2
	v_sub_u32_e32 v4, v3, v4
	v_add_u32_e32 v5, 1, v1
	v_cmp_ge_u32_e32 vcc, v4, v2
	v_add_u32_e32 v3, 1, v3
	s_nop 0
	v_cndmask_b32_e32 v1, v1, v5, vcc
	v_sub_u32_e32 v5, v4, v2
	v_cndmask_b32_e32 v4, v4, v5, vcc
	v_add_u32_e32 v5, 1, v1
	v_cmp_ge_u32_e32 vcc, v4, v2
	s_nop 1
	v_cndmask_b32_e32 v1, v1, v5, vcc
	v_mul_lo_u32 v4, v2, v1
	v_add_u32_e32 v2, v4, v2
	v_cmp_ne_u32_e32 vcc, v3, v2
	s_and_saveexec_b64 s[10:11], vcc
	s_xor_b64 s[10:11], exec, s[10:11]
	s_cbranch_execz .LBB0_46
	s_waitcnt lgkmcnt(0)
	s_waitcnt vmcnt(0)
	global_atomic_add v198, v199, s[8:9] offset:1152
	global_load_dword v0, v200, s[8:9] offset:1024 sc1
	s_add_u32 s14, s8, 0x2400
	s_addc_u32 s15, s9, 0
	s_waitcnt vmcnt(0)
	v_cmp_eq_u32_e32 vcc, v0, v1
	s_and_saveexec_b64 s[12:13], vcc
	s_cbranch_execz .LBB0_45
	s_mov_b32 s4, 1
	s_mov_b64 s[16:17], 0
	s_branch .LBB0_36

; __device__ __forceinline__ unsigned xb_ld(unsigned* p)              { return __hip_atomic_load(p, __ATOMIC_RELAXED, __HIP_MEMORY_SCOPE_AGENT); }
; __device__ __forceinline__ unsigned xb_add(unsigned* p, unsigned v) { return __hip_atomic_fetch_add(p, v, __ATOMIC_RELAXED, __HIP_MEMORY_SCOPE_AGENT); }
; #define XB_SPIN(cond, bar) do { unsigned _sp = 0; while (cond) { __builtin_amdgcn_s_sleep(1); \
;     if ((++_sp & 255u) == 0u) { if (xb_ld(&(bar)[XB_TMO])) break; if (_sp > XB_SPIN_CAP) { atomicAdd(&(bar)[XB_TMO], 1u); break; } } } } while (0)
; __device__ __forceinline__ void xcd_barrier(const XcdBarrier& b) {
;     ...
;     if (nloc == 0u) { xcd_barrier_complete(bar, b.x, nloc, nx); b.st[0] = nloc; b.st[1] = nx; }
;     const unsigned old = xb_add(&bar[XB_XSUB(b.x)], 1u);
;     const unsigned gen = old / nloc;
;     if (old + 1u == (gen + 1u) * nloc) {
;       __builtin_amdgcn_fence(__ATOMIC_RELEASE, "agent");
;       asm volatile("s_waitcnt vmcnt(0)" ::: "memory");
;       const unsigned og = xb_add(&bar[XB_TOP], 1u);
;       const unsigned tg = og / nx;
;       if (og + 1u == (tg + 1u) * nx) xb_add(&bar[XB_TOPGEN], 1u);
;       else XB_SPIN(xb_ld(&bar[XB_TOPGEN]) == tg, bar);
;       __builtin_amdgcn_fence(__ATOMIC_ACQUIRE, "agent");
;       xb_add(&bar[XB_XGEN(b.x)], 1u);
;       asm volatile("s_waitcnt vmcnt(0)" ::: "memory");
;     } else {
;       XB_SPIN(xb_ld(&bar[XB_XGEN(b.x)]) == gen, bar);
;       __builtin_amdgcn_fence(__ATOMIC_ACQUIRE, "agent");
;       asm volatile("s_waitcnt vmcnt(0)" ::: "memory");
;     }
.LBB0_45:
	s_or_b64 exec, exec, s[12:13]
	s_waitcnt vmcnt(0) lgkmcnt(0)
	s_waitcnt vmcnt(0)
.LBB0_46:
	s_andn2_saveexec_b64 s[10:11], s[10:11]
	s_cbranch_execz .LBB0_64
	v_mov_b32_e32 v5, v1
	v_sub_u32_e32 v6, v2, v1
	v_add_u32_e32 v6, -1, v6
	s_mov_b64 s[10:11], exec
	buffer_wbl2 sc1
	s_waitcnt lgkmcnt(0)
	s_waitcnt vmcnt(0)
	s_mov_b32 s4, 0
.Lxb_ipoll:
	global_load_dword v7, v198, s[8:9] offset:1152 sc1
	s_waitcnt vmcnt(0)
	v_cmp_eq_u32_e32 vcc, v7, v6
	s_nop 1
	s_cbranch_vccnz .Lxb_idone
	s_sleep 1
	s_add_u32 s4, s4, 1
	s_cmp_lt_u32 s4, 0x100000
	s_cbranch_scc1 .Lxb_ipoll
	v_readlane_b32 s12, v230, 31
	v_readlane_b32 s13, v230, 32
	s_nop 4
	global_atomic_add v135, v199, s[12:13]
.Lxb_idone:
	v_mbcnt_lo_u32_b32 v1, s10, 0
	v_mbcnt_hi_u32_b32 v1, s11, v1
	v_cmp_eq_u32_e32 vcc, 0, v1
	s_and_saveexec_b64 s[12:13], vcc
	s_cbranch_execz .LBB0_49
	s_bcnt1_i32_b64 s4, s[10:11]
	v_readlane_b32 s10, v230, 41
	v_mov_b32_e32 v2, s4
	v_readlane_b32 s11, v230, 42
	s_nop 4
	global_atomic_add v2, v135, v2, s[10:11] sc0
.LBB0_49:
	s_or_b64 exec, exec, s[12:13]
	s_waitcnt vmcnt(0)
	v_readfirstlane_b32 s4, v2
	v_cvt_f32_u32_e32 v2, v0
	v_sub_u32_e32 v3, 0, v0
	v_add_u32_e32 v1, s4, v1
	v_readlane_b32 s10, v230, 43
	v_rcp_iflag_f32_e32 v2, v2
	v_readlane_b32 s11, v230, 44
	s_mov_b64 s[12:13], -1
	v_mul_f32_e32 v2, 0x4f7ffffe, v2
	v_cvt_u32_f32_e32 v2, v2
	v_mul_lo_u32 v3, v3, v2
	v_mul_hi_u32 v3, v2, v3
	v_add_u32_e32 v2, v2, v3
	v_mul_hi_u32 v2, v1, v2
	v_mul_lo_u32 v3, v2, v0
	v_sub_u32_e32 v3, v1, v3
	v_cmp_ge_u32_e32 vcc, v3, v0
	v_add_u32_e32 v4, 1, v2
	v_add_u32_e32 v1, 1, v1
	v_cndmask_b32_e32 v2, v2, v4, vcc
	v_sub_u32_e32 v4, v3, v0
	v_cndmask_b32_e32 v3, v3, v4, vcc
	v_cmp_ge_u32_e32 vcc, v3, v0
	v_add_u32_e32 v3, 1, v2
	s_nop 0
	v_cndmask_b32_e32 v2, v2, v3, vcc
	v_mul_lo_u32 v3, v0, v2
	v_add_u32_e32 v0, v3, v0
	v_cmp_ne_u32_e32 vcc, v1, v0
	s_nop 1
	s_cbranch_vccnz .Lxb_wait
	v_mov_b32_e32 v0, 0x2400
	global_atomic_add v0, v199, s[34:35] offset:0
	global_atomic_add v0, v199, s[34:35] offset:256
	global_atomic_add v0, v199, s[34:35] offset:512
	global_atomic_add v0, v199, s[34:35] offset:768
	global_atomic_add v0, v199, s[34:35] offset:1024
	global_atomic_add v0, v199, s[34:35] offset:1280
	global_atomic_add v0, v199, s[34:35] offset:1536
	global_atomic_add v0, v199, s[34:35] offset:1792
	global_atomic_add v0, v199, s[34:35] offset:2048
	global_atomic_add v0, v199, s[34:35] offset:2304
	global_atomic_add v0, v199, s[34:35] offset:2560
	global_atomic_add v0, v199, s[34:35] offset:2816
	global_atomic_add v0, v199, s[34:35] offset:3072
	global_atomic_add v0, v199, s[34:35] offset:3328
	global_atomic_add v0, v199, s[34:35] offset:3584
	global_atomic_add v0, v199, s[34:35] offset:3840
	s_branch .Lxb_rel
.Lxb_wait:
	s_add_u32 s14, s8, 0x2400
	s_addc_u32 s15, s9, 0
	s_mov_b32 s4, 0
.Lxb_spin:
	global_load_dword v0, v135, s[14:15] sc1
	s_waitcnt vmcnt(0)
	v_cmp_ne_u32_e32 vcc, v0, v5
	s_nop 1
	s_cbranch_vccnz .Lxb_rel
	s_sleep 1
	s_add_u32 s4, s4, 1
	s_and_b32 s12, s4, 0xff
	s_cmp_lg_u32 s12, 0
	s_cbranch_scc1 .Lxb_spin
	v_readlane_b32 s12, v230, 31
	v_readlane_b32 s13, v230, 32
	s_nop 4
	global_load_dword v0, v135, s[12:13] sc1
	s_waitcnt vmcnt(0)
	v_cmp_ne_u32_e32 vcc, 0, v0
	s_nop 1
	s_cbranch_vccnz .Lxb_rel
	s_cmp_lt_u32 s4, 0x100000
	s_cbranch_scc1 .Lxb_spin
	global_atomic_add v135, v199, s[12:13]
.Lxb_rel:
	s_waitcnt vmcnt(0) lgkmcnt(0)
	s_waitcnt vmcnt(0)
